# topk main pass: candidate append uses index clamp instead of compare/exec/branch; slot 0/1 atomic completion deferred behind next slot arithmetic
# speedup vs baseline: 1.0124x; 1.0036x over previous
.LBB0_346:
	v_add_u32_e32 v243, 4, v31
	v_min_i32_e32 v0, s18, v243
	v_ashrrev_i32_e32 v1, 31, v0
	v_lshlrev_b64 v[0:1], 12, v[0:1]
	v_lshl_add_u64 v[0:1], v[154:155], 0, v[0:1]
	global_load_dwordx4 v[128:131], v[0:1], off
	global_load_dwordx4 v[116:119], v[0:1], off offset:1024
	global_load_dwordx4 v[120:123], v[0:1], off offset:2048
	global_load_dwordx4 v[124:127], v[0:1], off offset:3072
	s_waitcnt vmcnt(4)
	v_mfma_f32_32x32x16_f16 v[14:29], v[32:35], v[112:115], 0
	s_brev_b32 s4, 1
	v_cmp_le_i32_e32 vcc, v30, v238
	v_mfma_f32_32x32x16_f16 v[14:29], v[36:39], v[108:111], v[14:29]
	v_mfma_f32_32x32x16_f16 v[14:29], v[40:43], v[104:107], v[14:29]
	v_mfma_f32_32x32x16_f16 v[14:29], v[44:47], v[100:103], v[14:29]
	s_nop 11
	v_max_i32_e32 v0, 0, v14
	v_fma_f32 v244, v48, v0, 0
	v_max_i32_e32 v0, 0, v15
	v_fmac_f32_e32 v244, v49, v0
	v_max_i32_e32 v0, 0, v18
	v_fmac_f32_e32 v244, v50, v0
	v_max_i32_e32 v0, 0, v19
	v_fmac_f32_e32 v244, v51, v0
	v_max_i32_e32 v0, 0, v22
	v_fmac_f32_e32 v244, v52, v0
	v_max_i32_e32 v0, 0, v23
	v_fmac_f32_e32 v244, v53, v0
	v_max_i32_e32 v0, 0, v26
	v_fmac_f32_e32 v244, v54, v0
	v_max_i32_e32 v0, 0, v27
	v_fmac_f32_e32 v244, v55, v0
	v_mfma_f32_32x32x16_f16 v[0:15], v[64:67], v[112:115], 0
	v_ashrrev_i32_e32 v18, 31, v244
	v_bitop3_b32 v18, v18, v244, s4 bitop3:0x36
	s_waitcnt lgkmcnt(0)
	v_cmp_ge_u32_e64 s[4:5], v18, v96
	s_and_b64 s[6:7], vcc, s[4:5]
	v_mfma_f32_32x32x16_f16 v[0:15], v[68:71], v[108:111], v[0:15]
	v_mfma_f32_32x32x16_f16 v[0:15], v[72:75], v[104:107], v[0:15]
	v_mfma_f32_32x32x16_f16 v[0:15], v[76:79], v[100:103], v[0:15]
	s_mov_b64 s[22:23], s[6:7]
	s_and_saveexec_b64 s[4:5], s[6:7]
	v_add_u32_e32 v19, v139, v133
	ds_add_rtn_u32 v19, v19, v195 offset:57696
	s_or_b64 exec, exec, s[4:5]
	v_max_i32_e32 v16, 0, v16
	v_fma_f32 v16, v56, v16, 0
	v_max_i32_e32 v17, 0, v17
	v_fmac_f32_e32 v16, v57, v17
	v_max_i32_e32 v17, 0, v20
	v_fmac_f32_e32 v16, v58, v17
	v_max_i32_e32 v17, 0, v21
	v_fmac_f32_e32 v16, v59, v17
	v_max_i32_e32 v17, 0, v24
	v_fmac_f32_e32 v16, v60, v17
	v_max_i32_e32 v17, 0, v25
	v_fmac_f32_e32 v16, v61, v17
	v_max_i32_e32 v17, 0, v28
	v_fmac_f32_e32 v16, v62, v17
	v_max_i32_e32 v17, 0, v29
	v_fmac_f32_e32 v16, v63, v17
	v_ashrrev_i32_e32 v17, 31, v16
	s_brev_b32 s4, 1
	v_bitop3_b32 v16, v17, v16, s4 bitop3:0x36
	v_cmp_le_i32_e32 vcc, v30, v239
	v_cmp_ge_u32_e64 s[4:5], v16, v97
	s_and_b64 s[6:7], vcc, s[4:5]
	s_and_saveexec_b64 s[24:25], s[22:23]
	s_waitcnt lgkmcnt(0)
	v_min_u32_e32 v19, 0x3ff, v19
	v_lshl_add_u32 v22, v19, 2, v139
	v_add_lshl_u32 v19, v19, v173, 1
	v_sub_u32_e32 v19, v22, v19
	ds_write_b32 v22, v18
	ds_write_b16 v19, v30 offset:32768
	s_or_b64 exec, exec, s[24:25]
	s_mov_b64 s[22:23], s[6:7]
	s_and_saveexec_b64 s[4:5], s[6:7]
	v_add_u32_e32 v17, v139, v133
	ds_add_rtn_u32 v17, v17, v195 offset:57700
	s_or_b64 exec, exec, s[4:5]
	v_max_i32_e32 v0, 0, v0
	v_fma_f32 v0, v80, v0, 0
	v_max_i32_e32 v1, 0, v1
	v_fmac_f32_e32 v0, v81, v1
	v_max_i32_e32 v1, 0, v4
	v_fmac_f32_e32 v0, v82, v1
	v_max_i32_e32 v1, 0, v5
	v_fmac_f32_e32 v0, v83, v1
	v_max_i32_e32 v1, 0, v8
	v_fmac_f32_e32 v0, v84, v1
	v_max_i32_e32 v1, 0, v9
	v_fmac_f32_e32 v0, v85, v1
	v_max_i32_e32 v1, 0, v12
	v_fmac_f32_e32 v0, v86, v1
	v_max_i32_e32 v1, 0, v13
	v_fmac_f32_e32 v0, v87, v1
	v_ashrrev_i32_e32 v1, 31, v0
	s_brev_b32 s4, 1
	v_bitop3_b32 v0, v1, v0, s4 bitop3:0x36
	v_cmp_le_i32_e32 vcc, v30, v240
	v_cmp_ge_u32_e64 s[4:5], v0, v98
	s_and_b64 s[6:7], vcc, s[4:5]
	s_and_saveexec_b64 s[24:25], s[22:23]
	s_waitcnt lgkmcnt(0)
	v_min_u32_e32 v17, 0x3ff, v17
	v_add_u32_e32 v17, v17, v174
	v_lshlrev_b32_e32 v18, 2, v17
	v_lshlrev_b32_e32 v17, 1, v17
	v_sub_u32_e32 v17, v18, v17
	ds_write_b32 v18, v16
	ds_write_b16 v17, v30 offset:32768
	s_or_b64 exec, exec, s[24:25]
	s_and_saveexec_b64 s[4:5], s[6:7]
	s_cbranch_execz .LBB0_355
	v_add_u32_e32 v1, v139, v133
	ds_add_rtn_u32 v1, v1, v195 offset:57712
	s_movk_i32 s6, 0x400
	s_waitcnt lgkmcnt(0)
	v_min_u32_e32 v1, 0x3ff, v1
	v_add_u32_e32 v1, v1, v175
	v_lshlrev_b32_e32 v4, 2, v1
	v_lshlrev_b32_e32 v1, 1, v1
	v_sub_u32_e32 v1, v4, v1
	ds_write_b32 v4, v0
	ds_write_b16 v1, v30 offset:32768
.LBB0_355:
	s_or_b64 exec, exec, s[4:5]
	v_max_i32_e32 v0, 0, v2
	v_fma_f32 v0, v88, v0, 0
	v_max_i32_e32 v1, 0, v3
	v_fmac_f32_e32 v0, v89, v1
	v_max_i32_e32 v1, 0, v6
	v_fmac_f32_e32 v0, v90, v1
	v_max_i32_e32 v1, 0, v7
	v_fmac_f32_e32 v0, v91, v1
	v_max_i32_e32 v1, 0, v10
	v_fmac_f32_e32 v0, v92, v1
	v_max_i32_e32 v1, 0, v11
	v_fmac_f32_e32 v0, v93, v1
	v_max_i32_e32 v1, 0, v14
	v_fmac_f32_e32 v0, v94, v1
	v_max_i32_e32 v1, 0, v15
	v_fmac_f32_e32 v0, v95, v1
	v_ashrrev_i32_e32 v1, 31, v0
	s_brev_b32 s4, 1
	v_bitop3_b32 v0, v1, v0, s4 bitop3:0x36
	v_cmp_le_i32_e32 vcc, v30, v241
	v_cmp_ge_u32_e64 s[4:5], v0, v99
	s_and_b64 s[6:7], vcc, s[4:5]
	s_and_saveexec_b64 s[4:5], s[6:7]
	s_cbranch_execz .LBB0_358
	v_add_u32_e32 v1, v139, v133
	ds_add_rtn_u32 v1, v1, v195 offset:57716
	s_movk_i32 s6, 0x400
	s_waitcnt lgkmcnt(0)
	v_min_u32_e32 v1, 0x3ff, v1
	v_add_u32_e32 v1, v1, v178
	v_lshlrev_b32_e32 v2, 2, v1
	v_lshlrev_b32_e32 v1, 1, v1
	v_sub_u32_e32 v1, v2, v1
	ds_write_b32 v2, v0
	ds_write_b16 v1, v30 offset:32768
.LBB0_358:
	s_or_b64 exec, exec, s[4:5]
	v_add_u32_e32 v31, 8, v31
	v_min_i32_e32 v0, s18, v31
	v_ashrrev_i32_e32 v1, 31, v0
	v_lshlrev_b64 v[0:1], 12, v[0:1]
	v_lshl_add_u64 v[0:1], v[154:155], 0, v[0:1]
	global_load_dwordx4 v[112:115], v[0:1], off
	global_load_dwordx4 v[108:111], v[0:1], off offset:1024
	global_load_dwordx4 v[104:107], v[0:1], off offset:2048
	global_load_dwordx4 v[100:103], v[0:1], off offset:3072
	s_waitcnt vmcnt(7)
	v_mfma_f32_32x32x16_f16 v[14:29], v[32:35], v[128:131], 0
	s_brev_b32 s6, 1
	v_cmp_ge_i32_e64 s[4:5], s18, v243
	v_cmp_lt_i32_e32 vcc, s18, v243
	s_waitcnt vmcnt(6)
	v_mfma_f32_32x32x16_f16 v[14:29], v[36:39], v[116:119], v[14:29]
	s_waitcnt vmcnt(5)
	v_mfma_f32_32x32x16_f16 v[14:29], v[40:43], v[120:123], v[14:29]
	s_waitcnt vmcnt(4)
	v_mfma_f32_32x32x16_f16 v[14:29], v[44:47], v[124:127], v[14:29]
	s_nop 11
	v_max_i32_e32 v0, 0, v14
	v_fma_f32 v244, v48, v0, 0
	v_max_i32_e32 v0, 0, v15
	v_fmac_f32_e32 v244, v49, v0
	v_max_i32_e32 v0, 0, v18
	v_fmac_f32_e32 v244, v50, v0
	v_max_i32_e32 v0, 0, v19
	v_fmac_f32_e32 v244, v51, v0
	v_max_i32_e32 v0, 0, v22
	v_fmac_f32_e32 v244, v52, v0
	v_max_i32_e32 v0, 0, v23
	v_fmac_f32_e32 v244, v53, v0
	v_max_i32_e32 v0, 0, v26
	v_fmac_f32_e32 v244, v54, v0
	v_max_i32_e32 v0, 0, v27
	v_fmac_f32_e32 v244, v55, v0
	v_mfma_f32_32x32x16_f16 v[0:15], v[64:67], v[128:131], 0
	v_add_u32_e32 v18, 0x80, v30
	v_ashrrev_i32_e32 v19, 31, v244
	v_bitop3_b32 v19, v19, v244, s6 bitop3:0x36
	v_cmp_le_i32_e64 s[6:7], v18, v238
	s_and_b64 s[6:7], s[4:5], s[6:7]
	v_cmp_ge_u32_e64 s[4:5], v19, v96
	s_and_b64 s[4:5], s[6:7], s[4:5]
	v_mfma_f32_32x32x16_f16 v[0:15], v[68:71], v[116:119], v[0:15]
	v_mfma_f32_32x32x16_f16 v[0:15], v[72:75], v[120:123], v[0:15]
	v_mfma_f32_32x32x16_f16 v[0:15], v[76:79], v[124:127], v[0:15]
	s_mov_b64 s[22:23], s[4:5]
	s_and_saveexec_b64 s[6:7], s[4:5]
	v_add_u32_e32 v22, v139, v133
	ds_add_rtn_u32 v22, v22, v195 offset:57696
	s_or_b64 exec, exec, s[6:7]
	v_max_i32_e32 v16, 0, v16
	v_fma_f32 v16, v56, v16, 0
	v_max_i32_e32 v17, 0, v17
	v_fmac_f32_e32 v16, v57, v17
	v_max_i32_e32 v17, 0, v20
	v_fmac_f32_e32 v16, v58, v17
	v_max_i32_e32 v17, 0, v21
	v_fmac_f32_e32 v16, v59, v17
	v_max_i32_e32 v17, 0, v24
	v_fmac_f32_e32 v16, v60, v17
	v_max_i32_e32 v17, 0, v25
	v_fmac_f32_e32 v16, v61, v17
	v_max_i32_e32 v17, 0, v28
	v_fmac_f32_e32 v16, v62, v17
	v_max_i32_e32 v17, 0, v29
	v_fmac_f32_e32 v16, v63, v17
	v_ashrrev_i32_e32 v17, 31, v16
	s_brev_b32 s4, 1
	v_bitop3_b32 v16, v17, v16, s4 bitop3:0x36
	v_cmp_le_i32_e64 s[4:5], v18, v239
	s_xor_b64 s[6:7], vcc, -1
	s_and_b64 s[4:5], s[6:7], s[4:5]
	v_cmp_ge_u32_e32 vcc, v16, v97
	s_and_b64 s[10:11], s[4:5], vcc
	s_and_saveexec_b64 s[24:25], s[22:23]
	s_waitcnt lgkmcnt(0)
	v_min_u32_e32 v22, 0x3ff, v22
	v_lshl_add_u32 v23, v22, 2, v139
	v_add_lshl_u32 v22, v22, v173, 1
	v_sub_u32_e32 v22, v23, v22
	ds_write_b32 v23, v19
	ds_write_b16 v22, v18 offset:32768
	s_or_b64 exec, exec, s[24:25]
	s_mov_b64 s[22:23], s[10:11]
	s_and_saveexec_b64 s[4:5], s[10:11]
	v_add_u32_e32 v17, v139, v133
	ds_add_rtn_u32 v17, v17, v195 offset:57700
	s_or_b64 exec, exec, s[4:5]
	v_max_i32_e32 v0, 0, v0
	v_fma_f32 v0, v80, v0, 0
	v_max_i32_e32 v1, 0, v1
	v_fmac_f32_e32 v0, v81, v1
	v_max_i32_e32 v1, 0, v4
	v_fmac_f32_e32 v0, v82, v1
	v_max_i32_e32 v1, 0, v5
	v_fmac_f32_e32 v0, v83, v1
	v_max_i32_e32 v1, 0, v8
	v_fmac_f32_e32 v0, v84, v1
	v_max_i32_e32 v1, 0, v9
	v_fmac_f32_e32 v0, v85, v1
	v_max_i32_e32 v1, 0, v12
	v_fmac_f32_e32 v0, v86, v1
	v_max_i32_e32 v1, 0, v13
	v_fmac_f32_e32 v0, v87, v1
	v_ashrrev_i32_e32 v1, 31, v0
	s_brev_b32 s4, 1
	v_bitop3_b32 v0, v1, v0, s4 bitop3:0x36
	v_cmp_le_i32_e32 vcc, v18, v240
	s_and_b64 s[4:5], s[6:7], vcc
	v_cmp_ge_u32_e32 vcc, v0, v98
	s_and_b64 s[10:11], s[4:5], vcc
	s_and_saveexec_b64 s[24:25], s[22:23]
	s_waitcnt lgkmcnt(0)
	v_min_u32_e32 v17, 0x3ff, v17
	v_add_u32_e32 v17, v17, v174
	v_lshlrev_b32_e32 v19, 2, v17
	v_lshlrev_b32_e32 v17, 1, v17
	v_sub_u32_e32 v17, v19, v17
	ds_write_b32 v19, v16
	ds_write_b16 v17, v18 offset:32768
	s_or_b64 exec, exec, s[24:25]
	s_and_saveexec_b64 s[4:5], s[10:11]
	s_cbranch_execz .LBB0_367
	v_add_u32_e32 v1, v139, v133
	ds_add_rtn_u32 v1, v1, v195 offset:57712
	s_movk_i32 s10, 0x400
	s_waitcnt lgkmcnt(0)
	v_min_u32_e32 v1, 0x3ff, v1
	v_add_u32_e32 v1, v1, v175
	v_lshlrev_b32_e32 v4, 2, v1
	v_lshlrev_b32_e32 v1, 1, v1
	v_sub_u32_e32 v1, v4, v1
	ds_write_b32 v4, v0
	ds_write_b16 v1, v18 offset:32768
.LBB0_367:
	s_or_b64 exec, exec, s[4:5]
	v_max_i32_e32 v0, 0, v2
	v_fma_f32 v0, v88, v0, 0
	v_max_i32_e32 v1, 0, v3
	v_fmac_f32_e32 v0, v89, v1
	v_max_i32_e32 v1, 0, v6
	v_fmac_f32_e32 v0, v90, v1
	v_max_i32_e32 v1, 0, v7
	v_fmac_f32_e32 v0, v91, v1
	v_max_i32_e32 v1, 0, v10
	v_fmac_f32_e32 v0, v92, v1
	v_max_i32_e32 v1, 0, v11
	v_fmac_f32_e32 v0, v93, v1
	v_max_i32_e32 v1, 0, v14
	v_fmac_f32_e32 v0, v94, v1
	v_max_i32_e32 v1, 0, v15
	v_fmac_f32_e32 v0, v95, v1
	v_ashrrev_i32_e32 v1, 31, v0
	s_brev_b32 s4, 1
	v_bitop3_b32 v0, v1, v0, s4 bitop3:0x36
	v_cmp_le_i32_e32 vcc, v18, v241
	s_and_b64 s[4:5], s[6:7], vcc
	v_cmp_ge_u32_e32 vcc, v0, v99
	s_and_b64 s[6:7], s[4:5], vcc
	s_and_saveexec_b64 s[4:5], s[6:7]
	s_cbranch_execz .LBB0_345
	v_add_u32_e32 v1, v139, v133
	ds_add_rtn_u32 v1, v1, v195 offset:57716
	s_movk_i32 s6, 0x400
	s_waitcnt lgkmcnt(0)
	v_min_u32_e32 v1, 0x3ff, v1
	v_add_u32_e32 v1, v1, v178
	v_lshlrev_b32_e32 v2, 2, v1
	v_lshlrev_b32_e32 v1, 1, v1
	v_sub_u32_e32 v1, v2, v1
	ds_write_b32 v2, v0
	ds_write_b16 v1, v18 offset:32768
	s_branch .LBB0_345
